# grid-barrier poll loops: s_sleep 6 between counter polls (less polling pressure from idle workgroups during GEMM tails)
# speedup vs baseline: 1.0160x; 1.0094x over previous
.LBB0_141:
	s_sleep 6
	global_load_dword v0, v153, s[4:5] sc1
	s_waitcnt vmcnt(0)
	v_subrev_u32_e32 v0, s16, v0
	v_cmp_gt_i32_e32 vcc, 0, v0
	s_cbranch_vccnz .LBB0_141
	s_branch .LBB0_110

.LBB0_209:
	s_sleep 6
	global_load_dword v0, v153, s[4:5] sc1
	s_waitcnt vmcnt(0)
	v_subrev_u32_e32 v0, s22, v0
	v_cmp_gt_i32_e32 vcc, 0, v0
	s_cbranch_vccnz .LBB0_209

.LBB0_322:
	s_sleep 6
	global_load_dword v0, v153, s[4:5] sc1
	s_waitcnt vmcnt(0)
	v_subrev_u32_e32 v0, s62, v0
	v_cmp_gt_i32_e32 vcc, 0, v0
	s_cbranch_vccnz .LBB0_322

.LBB0_996:
	s_sleep 6
	global_load_dword v0, v153, s[4:5] sc1
	s_waitcnt vmcnt(0)
	v_subrev_u32_e32 v0, s6, v0
	v_cmp_gt_i32_e32 vcc, 0, v0
	s_cbranch_vccnz .LBB0_996

.LBB0_1119:
	s_sleep 6
	global_load_dword v0, v153, s[4:5] sc1
	s_waitcnt vmcnt(0)
	v_subrev_u32_e32 v0, s71, v0
	v_cmp_gt_i32_e32 vcc, 0, v0
	s_cbranch_vccnz .LBB0_1119
